# mixer phase combination: S5 pass-0 operands via direct HBM-to-LDS loads with counted waits, XCD-local work assignment for S5 and for the dilated-attention units, SB K/V fragment reads prefetched from
# baseline (speedup 1.0000x reference)
; DI int get_tid(int wv) { int l; asm volatile("v_mbcnt_lo_u32_b32 %0, -1, 0\n\tv_mbcnt_hi_u32_b32 %0, -1, %0" : "=v"(l)); return wv * 64 + l; }
; DI int get_bid() { int b = blockIdx.x; asm volatile("" : "+s"(b)); return b; }
; DI int get_grid() { int g = gridDim.x; asm volatile("" : "+s"(g)); return g; }
; DI int wave_of(int tid) { return __builtin_amdgcn_readfirstlane(tid >> 6); }
; DI void mix_dil(WVP u16* __restrict__ proj, float* __restrict__ lse, const float* __restrict__ rel_bias, char* smem) {
;   const int BID = get_bid(), GRD = get_grid();
;   const int tid = get_tid(WV), wave = wave_of(tid), lane = tid & 63, h = lane >> 5, l31 = lane & 31;
;   float* btab = (float*)smem;
;   char* vbuf = smem + 12 * 132 * 4 + wave * 4608;
;   __syncthreads();
;   for (int i = tid; i < 12 * 129; i += NTHR) {
;     int H = i / 129, ds = i % 129, g = H >> 2; int dil = g == 0 ? 1 : (g == 1 ? 4 : 16);
;     btab[H * 132 + ds] = rel_bias[t5_bucket(ds * dil) * 12 + H] * 1.44269504089f;
;   }
;   __syncthreads();
;   const float sc = 1.44269504089f * 0.125f;
;   const int i16 = lane & 15, tq = i16 >> 2, tp = i16 & 3, blk = (lane >> 4) & 1;
;     ...
;   bf16x8 bq_n[4], ak_n[4]; u32x4 vv_n[4];
;   const int u_first = BID * 8 + wave, u_step = GRD * 8, u_end = BATCH * 3 * 4 * 128;
.LBB0_330:
	s_and_b32 s1, s57, 7
	s_lshl_b32 s1, s1, 5
	s_lshr_b32 s0, s57, 3
	s_or_b32 s1, s1, s0
	s_mov_b32 s0, s53
	v_mbcnt_lo_u32_b32 v3, -1, 0
	v_mbcnt_hi_u32_b32 v3, -1, v3
	s_movk_i32 s5, 0x60c
	v_add_u32_e32 v4, s3, v3
	v_cmp_gt_i32_e32 vcc, s5, v4
	v_readfirstlane_b32 s4, v4
	s_barrier
	s_and_saveexec_b64 s[8:9], vcc
	s_mov_b32 s30, 0x3e38aa3b
	s_cbranch_execz .LBB0_335
	v_lshl_add_u32 v0, v4, 2, 0
	s_mov_b64 s[10:11], 0
	s_branch .LBB0_333
